# residual epilogue: f32 x stores staged through a per-wave LDS tile so each store instruction writes 8 full 128-byte lines (static LDS 16 KiB)
# speedup vs baseline: 1.0203x; 1.0133x over previous
.LBB0_874:
	s_cmpk_gt_i32 s56, 0x7f
	s_cbranch_scc1 .Lresid_orig
	s_and_b64 vcc, exec, s[10:11]
	s_cbranch_vccz .Lresid_nonorm
	v_readlane_b32 s62, v252, 7
	v_readlane_b32 s63, v252, 8
	s_lshr_b32 s20, s56, 4
	s_mul_i32 s20, s20, 0x6000
	s_add_u32 s44, s66, s20
	s_addc_u32 s45, s12, 0
	s_add_u32 s46, s13, s20
	s_addc_u32 s47, s26, 0
	s_mov_b32 s60, s38
	s_mov_b32 s61, s95
	v_lshl_or_b32 v236, s57, 8, v246
	v_lshl_add_u32 v237, s56, 8, v244
	v_lshlrev_b32_e32 v210, 2, v236
	v_lshl_add_u32 v211, v237, 12, v210
	v_and_b32_e32 v212, 4, v246
	v_mul_u32_u24_e32 v212, 6, v212
	v_lshl_add_u32 v212, v236, 1, v212
	v_lshl_add_u32 v212, v237, 11, v212
	v_lshlrev_b32_e32 v213, 2, v237
	v_lshlrev_b32_e32 v214, 2, v231
	v_lshlrev_b32_e32 v215, 2, v232
	v_and_b32_e32 v228, 63, v186
	v_lshrrev_b32_e32 v229, 6, v186
	v_lshlrev_b32_e32 v229, 11, v229
	v_add_u32_e32 v229, 0x20100, v229
	v_lshl_add_u32 v237, v228, 4, v229
	v_and_b32_e32 v236, 15, v244
	v_lshl_add_u32 v236, v236, 7, v229
	v_and_b32_e32 v229, 12, v246
	v_lshl_add_u32 v236, v229, 2, v236
	v_lshrrev_b32_e32 v214, 3, v228
	v_and_b32_e32 v229, 64, v244
	v_add_u32_e32 v214, v214, v229
	v_lshl_add_u32 v214, s56, 8, v214
	v_and_b32_e32 v228, 7, v228
	v_lshlrev_b32_e32 v228, 2, v228
	v_and_b32_e32 v229, 0x60, v246
	v_add_u32_e32 v228, v228, v229
	v_lshl_add_u32 v228, s57, 8, v228
	v_lshlrev_b32_e32 v228, 2, v228
	v_lshl_add_u32 v214, v214, 12, v228
	v_add_u32_e32 v215, 0x8000, v214
	global_load_dwordx4 v[60:63], v210, s[44:45] offset:0
	global_load_dwordx4 v[64:67], v210, s[44:45] offset:64
	global_load_dwordx4 v[68:71], v210, s[44:45] offset:512
	global_load_dwordx4 v[72:75], v210, s[44:45] offset:576
	global_load_dwordx4 v[148:151], v210, s[46:47] offset:0
	global_load_dwordx4 v[152:155], v210, s[46:47] offset:64
	global_load_dwordx4 v[156:159], v210, s[46:47] offset:512
	global_load_dwordx4 v[160:163], v210, s[46:47] offset:576
	global_load_dwordx4 v[194:197], v210, s[8:9] offset:0
	global_load_dwordx4 v[198:201], v210, s[8:9] offset:64
	global_load_dwordx4 v[202:205], v210, s[8:9] offset:512
	global_load_dwordx4 v[206:209], v210, s[8:9] offset:576
	s_mov_b32 s72, s60
	s_mov_b32 s73, s61
	global_load_dwordx4 v[164:167], v211, s[72:73] offset:0
	global_load_dwordx4 v[168:171], v211, s[72:73] offset:64
	global_load_dwordx4 v[172:175], v211, s[72:73] offset:512
	global_load_dwordx4 v[176:179], v211, s[72:73] offset:576
	s_waitcnt vmcnt(4)
	v_pk_add_f32 v[148:149], v[148:149], 1.0 op_sel_hi:[1,0]
	v_pk_add_f32 v[150:151], v[150:151], 1.0 op_sel_hi:[1,0]
	v_pk_mul_f32 v[148:149], v[194:195], v[148:149]
	v_pk_mul_f32 v[150:151], v[196:197], v[150:151]
	v_pk_add_f32 v[152:153], v[152:153], 1.0 op_sel_hi:[1,0]
	v_pk_add_f32 v[154:155], v[154:155], 1.0 op_sel_hi:[1,0]
	v_pk_mul_f32 v[152:153], v[198:199], v[152:153]
	v_pk_mul_f32 v[154:155], v[200:201], v[154:155]
	v_pk_add_f32 v[156:157], v[156:157], 1.0 op_sel_hi:[1,0]
	v_pk_add_f32 v[158:159], v[158:159], 1.0 op_sel_hi:[1,0]
	v_pk_mul_f32 v[156:157], v[202:203], v[156:157]
	v_pk_mul_f32 v[158:159], v[204:205], v[158:159]
	v_pk_add_f32 v[160:161], v[160:161], 1.0 op_sel_hi:[1,0]
	v_pk_add_f32 v[162:163], v[162:163], 1.0 op_sel_hi:[1,0]
	v_pk_mul_f32 v[160:161], v[206:207], v[160:161]
	v_pk_mul_f32 v[162:163], v[208:209], v[162:163]
	s_add_u32 s72, s60, 0x10000
	s_addc_u32 s73, s61, 0
	global_load_dwordx4 v[194:197], v211, s[72:73] offset:0
	global_load_dwordx4 v[198:201], v211, s[72:73] offset:64
	global_load_dwordx4 v[202:205], v211, s[72:73] offset:512
	global_load_dwordx4 v[206:209], v211, s[72:73] offset:576
	v_mov_b32_e32 v216, 0
	v_mov_b32_e32 v217, 0
	v_mov_b32_e32 v218, 0
	v_mov_b32_e32 v219, 0
	v_mov_b32_e32 v228, 0
	v_mov_b32_e32 v229, 0
	v_mov_b32_e32 v234, 0
	v_mov_b32_e32 v235, 0
	s_waitcnt vmcnt(4)
	s_mov_b32 s74, s62
	s_mov_b32 s75, s63
	s_mov_b32 s76, s88
	s_mov_b32 s77, s89
	v_pk_fma_f32 v[164:165], v[144:145], v[60:61], v[164:165]
	v_pk_fma_f32 v[166:167], v[146:147], v[62:63], v[166:167]
	v_pk_fma_f32 v[168:169], v[140:141], v[64:65], v[168:169]
	v_pk_fma_f32 v[170:171], v[142:143], v[66:67], v[170:171]
	ds_write_b128 v236, v[164:167]
	ds_write_b128 v236, v[168:171] offset:64
	v_fmac_f32_e32 v216, v164, v164
	v_fmac_f32_e32 v216, v165, v165
	v_fmac_f32_e32 v216, v166, v166
	v_fmac_f32_e32 v216, v167, v167
	v_pk_mul_f32 v[144:145], v[148:149], v[164:165]
	v_pk_mul_f32 v[146:147], v[150:151], v[166:167]
	v_fmac_f32_e32 v216, v168, v168
	v_fmac_f32_e32 v216, v169, v169
	v_fmac_f32_e32 v216, v170, v170
	v_fmac_f32_e32 v216, v171, v171
	v_pk_mul_f32 v[140:141], v[152:153], v[168:169]
	v_pk_mul_f32 v[142:143], v[154:155], v[170:171]
	s_waitcnt lgkmcnt(0)
	ds_read_b128 v[164:167], v237
	ds_read_b128 v[168:171], v237 offset:1024
	v_cvt_pk_bf16_f32 v144, v144, v145
	v_cvt_pk_bf16_f32 v145, v146, v147
	v_cvt_pk_bf16_f32 v146, v140, v141
	v_cvt_pk_bf16_f32 v147, v142, v143
	s_nop 1
	v_permlane16_swap_b32 v144, v146
	v_permlane16_swap_b32 v145, v147
	global_store_dwordx4 v212, v[144:147], s[76:77] offset:0
	s_waitcnt lgkmcnt(0)
	global_store_dwordx4 v214, v[164:167], s[74:75] offset:0
	global_store_dwordx4 v215, v[168:171], s[74:75] offset:0
	v_pk_fma_f32 v[172:173], v[136:137], v[68:69], v[172:173]
	v_pk_fma_f32 v[174:175], v[138:139], v[70:71], v[174:175]
	v_pk_fma_f32 v[176:177], v[132:133], v[72:73], v[176:177]
	v_pk_fma_f32 v[178:179], v[134:135], v[74:75], v[178:179]
	ds_write_b128 v236, v[172:175]
	ds_write_b128 v236, v[176:179] offset:64
	v_fmac_f32_e32 v216, v172, v172
	v_fmac_f32_e32 v216, v173, v173
	v_fmac_f32_e32 v216, v174, v174
	v_fmac_f32_e32 v216, v175, v175
	v_pk_mul_f32 v[136:137], v[156:157], v[172:173]
	v_pk_mul_f32 v[138:139], v[158:159], v[174:175]
	v_fmac_f32_e32 v216, v176, v176
	v_fmac_f32_e32 v216, v177, v177
	v_fmac_f32_e32 v216, v178, v178
	v_fmac_f32_e32 v216, v179, v179
	v_pk_mul_f32 v[132:133], v[160:161], v[176:177]
	v_pk_mul_f32 v[134:135], v[162:163], v[178:179]
	s_waitcnt lgkmcnt(0)
	ds_read_b128 v[172:175], v237
	ds_read_b128 v[176:179], v237 offset:1024
	v_cvt_pk_bf16_f32 v136, v136, v137
	v_cvt_pk_bf16_f32 v137, v138, v139
	v_cvt_pk_bf16_f32 v138, v132, v133
	v_cvt_pk_bf16_f32 v139, v134, v135
	s_nop 1
	v_permlane16_swap_b32 v136, v138
	v_permlane16_swap_b32 v137, v139
	global_store_dwordx4 v212, v[136:139], s[76:77] offset:256
	s_waitcnt lgkmcnt(0)
	global_store_dwordx4 v214, v[172:175], s[74:75] offset:512
	global_store_dwordx4 v215, v[176:179], s[74:75] offset:512
	s_add_u32 s72, s60, 0x20000
	s_addc_u32 s73, s61, 0
	global_load_dwordx4 v[164:167], v211, s[72:73] offset:0
	global_load_dwordx4 v[168:171], v211, s[72:73] offset:64
	global_load_dwordx4 v[172:175], v211, s[72:73] offset:512
	global_load_dwordx4 v[176:179], v211, s[72:73] offset:576
	s_add_u32 s72, s60, 0x30000
	s_addc_u32 s73, s61, 0
	global_load_dwordx4 v[144:147], v211, s[72:73] offset:0
	global_load_dwordx4 v[140:143], v211, s[72:73] offset:64
	global_load_dwordx4 v[136:139], v211, s[72:73] offset:512
	global_load_dwordx4 v[132:135], v211, s[72:73] offset:576
	s_waitcnt vmcnt(14)
	s_add_u32 s74, s62, 0x10000
	s_addc_u32 s75, s63, 0
	s_add_u32 s76, s88, 0x8000
	s_addc_u32 s77, s89, 0
	v_pk_fma_f32 v[194:195], v[128:129], v[60:61], v[194:195]
	v_pk_fma_f32 v[196:197], v[130:131], v[62:63], v[196:197]
	v_pk_fma_f32 v[198:199], v[124:125], v[64:65], v[198:199]
	v_pk_fma_f32 v[200:201], v[126:127], v[66:67], v[200:201]
	ds_write_b128 v236, v[194:197]
	ds_write_b128 v236, v[198:201] offset:64
	v_fmac_f32_e32 v217, v194, v194
	v_fmac_f32_e32 v217, v195, v195
	v_fmac_f32_e32 v217, v196, v196
	v_fmac_f32_e32 v217, v197, v197
	v_pk_mul_f32 v[128:129], v[148:149], v[194:195]
	v_pk_mul_f32 v[130:131], v[150:151], v[196:197]
	v_fmac_f32_e32 v217, v198, v198
	v_fmac_f32_e32 v217, v199, v199
	v_fmac_f32_e32 v217, v200, v200
	v_fmac_f32_e32 v217, v201, v201
	v_pk_mul_f32 v[124:125], v[152:153], v[198:199]
	v_pk_mul_f32 v[126:127], v[154:155], v[200:201]
	s_waitcnt lgkmcnt(0)
	ds_read_b128 v[194:197], v237
	ds_read_b128 v[198:201], v237 offset:1024
	v_cvt_pk_bf16_f32 v128, v128, v129
	v_cvt_pk_bf16_f32 v129, v130, v131
	v_cvt_pk_bf16_f32 v130, v124, v125
	v_cvt_pk_bf16_f32 v131, v126, v127
	s_nop 1
	v_permlane16_swap_b32 v128, v130
	v_permlane16_swap_b32 v129, v131
	global_store_dwordx4 v212, v[128:131], s[76:77] offset:0
	s_waitcnt lgkmcnt(0)
	global_store_dwordx4 v214, v[194:197], s[74:75] offset:0
	global_store_dwordx4 v215, v[198:201], s[74:75] offset:0
	v_pk_fma_f32 v[202:203], v[120:121], v[68:69], v[202:203]
	v_pk_fma_f32 v[204:205], v[122:123], v[70:71], v[204:205]
	v_pk_fma_f32 v[206:207], v[116:117], v[72:73], v[206:207]
	v_pk_fma_f32 v[208:209], v[118:119], v[74:75], v[208:209]
	ds_write_b128 v236, v[202:205]
	ds_write_b128 v236, v[206:209] offset:64
	v_fmac_f32_e32 v217, v202, v202
	v_fmac_f32_e32 v217, v203, v203
	v_fmac_f32_e32 v217, v204, v204
	v_fmac_f32_e32 v217, v205, v205
	v_pk_mul_f32 v[120:121], v[156:157], v[202:203]
	v_pk_mul_f32 v[122:123], v[158:159], v[204:205]
	v_fmac_f32_e32 v217, v206, v206
	v_fmac_f32_e32 v217, v207, v207
	v_fmac_f32_e32 v217, v208, v208
	v_fmac_f32_e32 v217, v209, v209
	v_pk_mul_f32 v[116:117], v[160:161], v[206:207]
	v_pk_mul_f32 v[118:119], v[162:163], v[208:209]
	s_waitcnt lgkmcnt(0)
	ds_read_b128 v[202:205], v237
	ds_read_b128 v[206:209], v237 offset:1024
	v_cvt_pk_bf16_f32 v120, v120, v121
	v_cvt_pk_bf16_f32 v121, v122, v123
	v_cvt_pk_bf16_f32 v122, v116, v117
	v_cvt_pk_bf16_f32 v123, v118, v119
	s_nop 1
	v_permlane16_swap_b32 v120, v122
	v_permlane16_swap_b32 v121, v123
	global_store_dwordx4 v212, v[120:123], s[76:77] offset:256
	s_waitcnt lgkmcnt(0)
	global_store_dwordx4 v214, v[202:205], s[74:75] offset:512
	global_store_dwordx4 v215, v[206:209], s[74:75] offset:512
	s_add_u32 s72, s60, 0x80000
	s_addc_u32 s73, s61, 0
	global_load_dwordx4 v[194:197], v211, s[72:73] offset:0
	global_load_dwordx4 v[198:201], v211, s[72:73] offset:64
	global_load_dwordx4 v[202:205], v211, s[72:73] offset:512
	global_load_dwordx4 v[206:209], v211, s[72:73] offset:576
	s_add_u32 s72, s60, 0x90000
	s_addc_u32 s73, s61, 0
	global_load_dwordx4 v[128:131], v211, s[72:73] offset:0
	global_load_dwordx4 v[124:127], v211, s[72:73] offset:64
	global_load_dwordx4 v[120:123], v211, s[72:73] offset:512
	global_load_dwordx4 v[116:119], v211, s[72:73] offset:576
	s_waitcnt vmcnt(18)
	s_add_u32 s74, s62, 0x20000
	s_addc_u32 s75, s63, 0
	s_add_u32 s76, s88, 0x10000
	s_addc_u32 s77, s89, 0
	v_pk_fma_f32 v[164:165], v[112:113], v[60:61], v[164:165]
	v_pk_fma_f32 v[166:167], v[114:115], v[62:63], v[166:167]
	v_pk_fma_f32 v[168:169], v[108:109], v[64:65], v[168:169]
	v_pk_fma_f32 v[170:171], v[110:111], v[66:67], v[170:171]
	ds_write_b128 v236, v[164:167]
	ds_write_b128 v236, v[168:171] offset:64
	v_fmac_f32_e32 v218, v164, v164
	v_fmac_f32_e32 v218, v165, v165
	v_fmac_f32_e32 v218, v166, v166
	v_fmac_f32_e32 v218, v167, v167
	v_pk_mul_f32 v[112:113], v[148:149], v[164:165]
	v_pk_mul_f32 v[114:115], v[150:151], v[166:167]
	v_fmac_f32_e32 v218, v168, v168
	v_fmac_f32_e32 v218, v169, v169
	v_fmac_f32_e32 v218, v170, v170
	v_fmac_f32_e32 v218, v171, v171
	v_pk_mul_f32 v[108:109], v[152:153], v[168:169]
	v_pk_mul_f32 v[110:111], v[154:155], v[170:171]
	s_waitcnt lgkmcnt(0)
	ds_read_b128 v[164:167], v237
	ds_read_b128 v[168:171], v237 offset:1024
	v_cvt_pk_bf16_f32 v112, v112, v113
	v_cvt_pk_bf16_f32 v113, v114, v115
	v_cvt_pk_bf16_f32 v114, v108, v109
	v_cvt_pk_bf16_f32 v115, v110, v111
	s_nop 1
	v_permlane16_swap_b32 v112, v114
	v_permlane16_swap_b32 v113, v115
	global_store_dwordx4 v212, v[112:115], s[76:77] offset:0
	s_waitcnt lgkmcnt(0)
	global_store_dwordx4 v214, v[164:167], s[74:75] offset:0
	global_store_dwordx4 v215, v[168:171], s[74:75] offset:0
	v_pk_fma_f32 v[172:173], v[104:105], v[68:69], v[172:173]
	v_pk_fma_f32 v[174:175], v[106:107], v[70:71], v[174:175]
	v_pk_fma_f32 v[176:177], v[100:101], v[72:73], v[176:177]
	v_pk_fma_f32 v[178:179], v[102:103], v[74:75], v[178:179]
	ds_write_b128 v236, v[172:175]
	ds_write_b128 v236, v[176:179] offset:64
	v_fmac_f32_e32 v218, v172, v172
	v_fmac_f32_e32 v218, v173, v173
	v_fmac_f32_e32 v218, v174, v174
	v_fmac_f32_e32 v218, v175, v175
	v_pk_mul_f32 v[104:105], v[156:157], v[172:173]
	v_pk_mul_f32 v[106:107], v[158:159], v[174:175]
	v_fmac_f32_e32 v218, v176, v176
	v_fmac_f32_e32 v218, v177, v177
	v_fmac_f32_e32 v218, v178, v178
	v_fmac_f32_e32 v218, v179, v179
	v_pk_mul_f32 v[100:101], v[160:161], v[176:177]
	v_pk_mul_f32 v[102:103], v[162:163], v[178:179]
	s_waitcnt lgkmcnt(0)
	ds_read_b128 v[172:175], v237
	ds_read_b128 v[176:179], v237 offset:1024
	v_cvt_pk_bf16_f32 v104, v104, v105
	v_cvt_pk_bf16_f32 v105, v106, v107
	v_cvt_pk_bf16_f32 v106, v100, v101
	v_cvt_pk_bf16_f32 v107, v102, v103
	s_nop 1
	v_permlane16_swap_b32 v104, v106
	v_permlane16_swap_b32 v105, v107
	global_store_dwordx4 v212, v[104:107], s[76:77] offset:256
	s_waitcnt lgkmcnt(0)
	global_store_dwordx4 v214, v[172:175], s[74:75] offset:512
	global_store_dwordx4 v215, v[176:179], s[74:75] offset:512
	s_add_u32 s72, s60, 0xa0000
	s_addc_u32 s73, s61, 0
	global_load_dwordx4 v[164:167], v211, s[72:73] offset:0
	global_load_dwordx4 v[168:171], v211, s[72:73] offset:64
	global_load_dwordx4 v[172:175], v211, s[72:73] offset:512
	global_load_dwordx4 v[176:179], v211, s[72:73] offset:576
	s_add_u32 s72, s60, 0xb0000
	s_addc_u32 s73, s61, 0
	global_load_dwordx4 v[112:115], v211, s[72:73] offset:0
	global_load_dwordx4 v[108:111], v211, s[72:73] offset:64
	global_load_dwordx4 v[104:107], v211, s[72:73] offset:512
	global_load_dwordx4 v[100:103], v211, s[72:73] offset:576
	s_waitcnt vmcnt(28)
	s_add_u32 s74, s62, 0x30000
	s_addc_u32 s75, s63, 0
	s_add_u32 s76, s88, 0x18000
	s_addc_u32 s77, s89, 0
	v_pk_fma_f32 v[144:145], v[92:93], v[60:61], v[144:145]
	v_pk_fma_f32 v[146:147], v[94:95], v[62:63], v[146:147]
	v_pk_fma_f32 v[140:141], v[88:89], v[64:65], v[140:141]
	v_pk_fma_f32 v[142:143], v[90:91], v[66:67], v[142:143]
	ds_write_b128 v236, v[144:147]
	ds_write_b128 v236, v[140:143] offset:64
	v_fmac_f32_e32 v219, v144, v144
	v_fmac_f32_e32 v219, v145, v145
	v_fmac_f32_e32 v219, v146, v146
	v_fmac_f32_e32 v219, v147, v147
	v_pk_mul_f32 v[92:93], v[148:149], v[144:145]
	v_pk_mul_f32 v[94:95], v[150:151], v[146:147]
	v_fmac_f32_e32 v219, v140, v140
	v_fmac_f32_e32 v219, v141, v141
	v_fmac_f32_e32 v219, v142, v142
	v_fmac_f32_e32 v219, v143, v143
	v_pk_mul_f32 v[88:89], v[152:153], v[140:141]
	v_pk_mul_f32 v[90:91], v[154:155], v[142:143]
	s_waitcnt lgkmcnt(0)
	ds_read_b128 v[144:147], v237
	ds_read_b128 v[140:143], v237 offset:1024
	v_cvt_pk_bf16_f32 v92, v92, v93
	v_cvt_pk_bf16_f32 v93, v94, v95
	v_cvt_pk_bf16_f32 v94, v88, v89
	v_cvt_pk_bf16_f32 v95, v90, v91
	s_nop 1
	v_permlane16_swap_b32 v92, v94
	v_permlane16_swap_b32 v93, v95
	global_store_dwordx4 v212, v[92:95], s[76:77] offset:0
	s_waitcnt lgkmcnt(0)
	global_store_dwordx4 v214, v[144:147], s[74:75] offset:0
	global_store_dwordx4 v215, v[140:143], s[74:75] offset:0
	v_pk_fma_f32 v[136:137], v[84:85], v[68:69], v[136:137]
	v_pk_fma_f32 v[138:139], v[86:87], v[70:71], v[138:139]
	v_pk_fma_f32 v[132:133], v[80:81], v[72:73], v[132:133]
	v_pk_fma_f32 v[134:135], v[82:83], v[74:75], v[134:135]
	ds_write_b128 v236, v[136:139]
	ds_write_b128 v236, v[132:135] offset:64
	v_fmac_f32_e32 v219, v136, v136
	v_fmac_f32_e32 v219, v137, v137
	v_fmac_f32_e32 v219, v138, v138
	v_fmac_f32_e32 v219, v139, v139
	v_pk_mul_f32 v[84:85], v[156:157], v[136:137]
	v_pk_mul_f32 v[86:87], v[158:159], v[138:139]
	v_fmac_f32_e32 v219, v132, v132
	v_fmac_f32_e32 v219, v133, v133
	v_fmac_f32_e32 v219, v134, v134
	v_fmac_f32_e32 v219, v135, v135
	v_pk_mul_f32 v[80:81], v[160:161], v[132:133]
	v_pk_mul_f32 v[82:83], v[162:163], v[134:135]
	s_waitcnt lgkmcnt(0)
	ds_read_b128 v[136:139], v237
	ds_read_b128 v[132:135], v237 offset:1024
	v_cvt_pk_bf16_f32 v84, v84, v85
	v_cvt_pk_bf16_f32 v85, v86, v87
	v_cvt_pk_bf16_f32 v86, v80, v81
	v_cvt_pk_bf16_f32 v87, v82, v83
	s_nop 1
	v_permlane16_swap_b32 v84, v86
	v_permlane16_swap_b32 v85, v87
	global_store_dwordx4 v212, v[84:87], s[76:77] offset:256
	s_waitcnt lgkmcnt(0)
	global_store_dwordx4 v214, v[136:139], s[74:75] offset:512
	global_store_dwordx4 v215, v[132:135], s[74:75] offset:512
	s_waitcnt vmcnt(24)
	s_add_u32 s74, s62, 0x80000
	s_addc_u32 s75, s63, 0
	s_add_u32 s76, s88, 0x40000
	s_addc_u32 s77, s89, 0
	v_pk_fma_f32 v[194:195], v[76:77], v[60:61], v[194:195]
	v_pk_fma_f32 v[196:197], v[78:79], v[62:63], v[196:197]
	v_pk_fma_f32 v[198:199], v[56:57], v[64:65], v[198:199]
	v_pk_fma_f32 v[200:201], v[58:59], v[66:67], v[200:201]
	ds_write_b128 v236, v[194:197]
	ds_write_b128 v236, v[198:201] offset:64
	v_fmac_f32_e32 v228, v194, v194
	v_fmac_f32_e32 v228, v195, v195
	v_fmac_f32_e32 v228, v196, v196
	v_fmac_f32_e32 v228, v197, v197
	v_pk_mul_f32 v[76:77], v[148:149], v[194:195]
	v_pk_mul_f32 v[78:79], v[150:151], v[196:197]
	v_fmac_f32_e32 v228, v198, v198
	v_fmac_f32_e32 v228, v199, v199
	v_fmac_f32_e32 v228, v200, v200
	v_fmac_f32_e32 v228, v201, v201
	v_pk_mul_f32 v[56:57], v[152:153], v[198:199]
	v_pk_mul_f32 v[58:59], v[154:155], v[200:201]
	s_waitcnt lgkmcnt(0)
	ds_read_b128 v[194:197], v237
	ds_read_b128 v[198:201], v237 offset:1024
	v_cvt_pk_bf16_f32 v76, v76, v77
	v_cvt_pk_bf16_f32 v77, v78, v79
	v_cvt_pk_bf16_f32 v78, v56, v57
	v_cvt_pk_bf16_f32 v79, v58, v59
	s_nop 1
	v_permlane16_swap_b32 v76, v78
	v_permlane16_swap_b32 v77, v79
	global_store_dwordx4 v212, v[76:79], s[76:77] offset:0
	s_waitcnt lgkmcnt(0)
	global_store_dwordx4 v214, v[194:197], s[74:75] offset:0
	global_store_dwordx4 v215, v[198:201], s[74:75] offset:0
	v_pk_fma_f32 v[202:203], v[52:53], v[68:69], v[202:203]
	v_pk_fma_f32 v[204:205], v[54:55], v[70:71], v[204:205]
	v_pk_fma_f32 v[206:207], v[48:49], v[72:73], v[206:207]
	v_pk_fma_f32 v[208:209], v[50:51], v[74:75], v[208:209]
	ds_write_b128 v236, v[202:205]
	ds_write_b128 v236, v[206:209] offset:64
	v_fmac_f32_e32 v228, v202, v202
	v_fmac_f32_e32 v228, v203, v203
	v_fmac_f32_e32 v228, v204, v204
	v_fmac_f32_e32 v228, v205, v205
	v_pk_mul_f32 v[52:53], v[156:157], v[202:203]
	v_pk_mul_f32 v[54:55], v[158:159], v[204:205]
	v_fmac_f32_e32 v228, v206, v206
	v_fmac_f32_e32 v228, v207, v207
	v_fmac_f32_e32 v228, v208, v208
	v_fmac_f32_e32 v228, v209, v209
	v_pk_mul_f32 v[48:49], v[160:161], v[206:207]
	v_pk_mul_f32 v[50:51], v[162:163], v[208:209]
	s_waitcnt lgkmcnt(0)
	ds_read_b128 v[202:205], v237
	ds_read_b128 v[206:209], v237 offset:1024
	v_cvt_pk_bf16_f32 v52, v52, v53
	v_cvt_pk_bf16_f32 v53, v54, v55
	v_cvt_pk_bf16_f32 v54, v48, v49
	v_cvt_pk_bf16_f32 v55, v50, v51
	s_nop 1
	v_permlane16_swap_b32 v52, v54
	v_permlane16_swap_b32 v53, v55
	global_store_dwordx4 v212, v[52:55], s[76:77] offset:256
	s_waitcnt lgkmcnt(0)
	global_store_dwordx4 v214, v[202:205], s[74:75] offset:512
	global_store_dwordx4 v215, v[206:209], s[74:75] offset:512
	s_waitcnt vmcnt(26)
	s_add_u32 s74, s62, 0x90000
	s_addc_u32 s75, s63, 0
	s_add_u32 s76, s88, 0x48000
	s_addc_u32 s77, s89, 0
	v_pk_fma_f32 v[128:129], v[44:45], v[60:61], v[128:129]
	v_pk_fma_f32 v[130:131], v[46:47], v[62:63], v[130:131]
	v_pk_fma_f32 v[124:125], v[40:41], v[64:65], v[124:125]
	v_pk_fma_f32 v[126:127], v[42:43], v[66:67], v[126:127]
	ds_write_b128 v236, v[128:131]
	ds_write_b128 v236, v[124:127] offset:64
	v_fmac_f32_e32 v229, v128, v128
	v_fmac_f32_e32 v229, v129, v129
	v_fmac_f32_e32 v229, v130, v130
	v_fmac_f32_e32 v229, v131, v131
	v_pk_mul_f32 v[44:45], v[148:149], v[128:129]
	v_pk_mul_f32 v[46:47], v[150:151], v[130:131]
	v_fmac_f32_e32 v229, v124, v124
	v_fmac_f32_e32 v229, v125, v125
	v_fmac_f32_e32 v229, v126, v126
	v_fmac_f32_e32 v229, v127, v127
	v_pk_mul_f32 v[40:41], v[152:153], v[124:125]
	v_pk_mul_f32 v[42:43], v[154:155], v[126:127]
	s_waitcnt lgkmcnt(0)
	ds_read_b128 v[128:131], v237
	ds_read_b128 v[124:127], v237 offset:1024
	v_cvt_pk_bf16_f32 v44, v44, v45
	v_cvt_pk_bf16_f32 v45, v46, v47
	v_cvt_pk_bf16_f32 v46, v40, v41
	v_cvt_pk_bf16_f32 v47, v42, v43
	s_nop 1
	v_permlane16_swap_b32 v44, v46
	v_permlane16_swap_b32 v45, v47
	global_store_dwordx4 v212, v[44:47], s[76:77] offset:0
	s_waitcnt lgkmcnt(0)
	global_store_dwordx4 v214, v[128:131], s[74:75] offset:0
	global_store_dwordx4 v215, v[124:127], s[74:75] offset:0
	v_pk_fma_f32 v[120:121], v[36:37], v[68:69], v[120:121]
	v_pk_fma_f32 v[122:123], v[38:39], v[70:71], v[122:123]
	v_pk_fma_f32 v[116:117], v[32:33], v[72:73], v[116:117]
	v_pk_fma_f32 v[118:119], v[34:35], v[74:75], v[118:119]
	ds_write_b128 v236, v[120:123]
	ds_write_b128 v236, v[116:119] offset:64
	v_fmac_f32_e32 v229, v120, v120
	v_fmac_f32_e32 v229, v121, v121
	v_fmac_f32_e32 v229, v122, v122
	v_fmac_f32_e32 v229, v123, v123
	v_pk_mul_f32 v[36:37], v[156:157], v[120:121]
	v_pk_mul_f32 v[38:39], v[158:159], v[122:123]
	v_fmac_f32_e32 v229, v116, v116
	v_fmac_f32_e32 v229, v117, v117
	v_fmac_f32_e32 v229, v118, v118
	v_fmac_f32_e32 v229, v119, v119
	v_pk_mul_f32 v[32:33], v[160:161], v[116:117]
	v_pk_mul_f32 v[34:35], v[162:163], v[118:119]
	s_waitcnt lgkmcnt(0)
	ds_read_b128 v[120:123], v237
	ds_read_b128 v[116:119], v237 offset:1024
	v_cvt_pk_bf16_f32 v36, v36, v37
	v_cvt_pk_bf16_f32 v37, v38, v39
	v_cvt_pk_bf16_f32 v38, v32, v33
	v_cvt_pk_bf16_f32 v39, v34, v35
	s_nop 1
	v_permlane16_swap_b32 v36, v38
	v_permlane16_swap_b32 v37, v39
	global_store_dwordx4 v212, v[36:39], s[76:77] offset:256
	s_waitcnt lgkmcnt(0)
	global_store_dwordx4 v214, v[120:123], s[74:75] offset:512
	global_store_dwordx4 v215, v[116:119], s[74:75] offset:512
	s_waitcnt vmcnt(22)
	s_add_u32 s74, s62, 0xa0000
	s_addc_u32 s75, s63, 0
	s_add_u32 s76, s88, 0x50000
	s_addc_u32 s77, s89, 0
	v_pk_fma_f32 v[164:165], v[28:29], v[60:61], v[164:165]
	v_pk_fma_f32 v[166:167], v[30:31], v[62:63], v[166:167]
	v_pk_fma_f32 v[168:169], v[24:25], v[64:65], v[168:169]
	v_pk_fma_f32 v[170:171], v[26:27], v[66:67], v[170:171]
	ds_write_b128 v236, v[164:167]
	ds_write_b128 v236, v[168:171] offset:64
	v_fmac_f32_e32 v234, v164, v164
	v_fmac_f32_e32 v234, v165, v165
	v_fmac_f32_e32 v234, v166, v166
	v_fmac_f32_e32 v234, v167, v167
	v_pk_mul_f32 v[28:29], v[148:149], v[164:165]
	v_pk_mul_f32 v[30:31], v[150:151], v[166:167]
	v_fmac_f32_e32 v234, v168, v168
	v_fmac_f32_e32 v234, v169, v169
	v_fmac_f32_e32 v234, v170, v170
	v_fmac_f32_e32 v234, v171, v171
	v_pk_mul_f32 v[24:25], v[152:153], v[168:169]
	v_pk_mul_f32 v[26:27], v[154:155], v[170:171]
	s_waitcnt lgkmcnt(0)
	ds_read_b128 v[164:167], v237
	ds_read_b128 v[168:171], v237 offset:1024
	v_cvt_pk_bf16_f32 v28, v28, v29
	v_cvt_pk_bf16_f32 v29, v30, v31
	v_cvt_pk_bf16_f32 v30, v24, v25
	v_cvt_pk_bf16_f32 v31, v26, v27
	s_nop 1
	v_permlane16_swap_b32 v28, v30
	v_permlane16_swap_b32 v29, v31
	global_store_dwordx4 v212, v[28:31], s[76:77] offset:0
	s_waitcnt lgkmcnt(0)
	global_store_dwordx4 v214, v[164:167], s[74:75] offset:0
	global_store_dwordx4 v215, v[168:171], s[74:75] offset:0
	v_pk_fma_f32 v[172:173], v[20:21], v[68:69], v[172:173]
	v_pk_fma_f32 v[174:175], v[22:23], v[70:71], v[174:175]
	v_pk_fma_f32 v[176:177], v[16:17], v[72:73], v[176:177]
	v_pk_fma_f32 v[178:179], v[18:19], v[74:75], v[178:179]
	ds_write_b128 v236, v[172:175]
	ds_write_b128 v236, v[176:179] offset:64
	v_fmac_f32_e32 v234, v172, v172
	v_fmac_f32_e32 v234, v173, v173
	v_fmac_f32_e32 v234, v174, v174
	v_fmac_f32_e32 v234, v175, v175
	v_pk_mul_f32 v[20:21], v[156:157], v[172:173]
	v_pk_mul_f32 v[22:23], v[158:159], v[174:175]
	v_fmac_f32_e32 v234, v176, v176
	v_fmac_f32_e32 v234, v177, v177
	v_fmac_f32_e32 v234, v178, v178
	v_fmac_f32_e32 v234, v179, v179
	v_pk_mul_f32 v[16:17], v[160:161], v[176:177]
	v_pk_mul_f32 v[18:19], v[162:163], v[178:179]
	s_waitcnt lgkmcnt(0)
	ds_read_b128 v[172:175], v237
	ds_read_b128 v[176:179], v237 offset:1024
	v_cvt_pk_bf16_f32 v20, v20, v21
	v_cvt_pk_bf16_f32 v21, v22, v23
	v_cvt_pk_bf16_f32 v22, v16, v17
	v_cvt_pk_bf16_f32 v23, v18, v19
	s_nop 1
	v_permlane16_swap_b32 v20, v22
	v_permlane16_swap_b32 v21, v23
	global_store_dwordx4 v212, v[20:23], s[76:77] offset:256
	s_waitcnt lgkmcnt(0)
	global_store_dwordx4 v214, v[172:175], s[74:75] offset:512
	global_store_dwordx4 v215, v[176:179], s[74:75] offset:512
	s_waitcnt vmcnt(24)
	s_add_u32 s74, s62, 0xb0000
	s_addc_u32 s75, s63, 0
	s_add_u32 s76, s88, 0x58000
	s_addc_u32 s77, s89, 0
	v_pk_fma_f32 v[112:113], v[12:13], v[60:61], v[112:113]
	v_pk_fma_f32 v[114:115], v[14:15], v[62:63], v[114:115]
	v_pk_fma_f32 v[108:109], v[8:9], v[64:65], v[108:109]
	v_pk_fma_f32 v[110:111], v[10:11], v[66:67], v[110:111]
	ds_write_b128 v236, v[112:115]
	ds_write_b128 v236, v[108:111] offset:64
	v_fmac_f32_e32 v235, v112, v112
	v_fmac_f32_e32 v235, v113, v113
	v_fmac_f32_e32 v235, v114, v114
	v_fmac_f32_e32 v235, v115, v115
	v_pk_mul_f32 v[12:13], v[148:149], v[112:113]
	v_pk_mul_f32 v[14:15], v[150:151], v[114:115]
	v_fmac_f32_e32 v235, v108, v108
	v_fmac_f32_e32 v235, v109, v109
	v_fmac_f32_e32 v235, v110, v110
	v_fmac_f32_e32 v235, v111, v111
	v_pk_mul_f32 v[8:9], v[152:153], v[108:109]
	v_pk_mul_f32 v[10:11], v[154:155], v[110:111]
	s_waitcnt lgkmcnt(0)
	ds_read_b128 v[112:115], v237
	ds_read_b128 v[108:111], v237 offset:1024
	v_cvt_pk_bf16_f32 v12, v12, v13
	v_cvt_pk_bf16_f32 v13, v14, v15
	v_cvt_pk_bf16_f32 v14, v8, v9
	v_cvt_pk_bf16_f32 v15, v10, v11
	s_nop 1
	v_permlane16_swap_b32 v12, v14
	v_permlane16_swap_b32 v13, v15
	global_store_dwordx4 v212, v[12:15], s[76:77] offset:0
	s_waitcnt lgkmcnt(0)
	global_store_dwordx4 v214, v[112:115], s[74:75] offset:0
	global_store_dwordx4 v215, v[108:111], s[74:75] offset:0
	v_pk_fma_f32 v[104:105], v[4:5], v[68:69], v[104:105]
	v_pk_fma_f32 v[106:107], v[6:7], v[70:71], v[106:107]
	v_pk_fma_f32 v[100:101], v[0:1], v[72:73], v[100:101]
	v_pk_fma_f32 v[102:103], v[2:3], v[74:75], v[102:103]
	ds_write_b128 v236, v[104:107]
	ds_write_b128 v236, v[100:103] offset:64
	v_fmac_f32_e32 v235, v104, v104
	v_fmac_f32_e32 v235, v105, v105
	v_fmac_f32_e32 v235, v106, v106
	v_fmac_f32_e32 v235, v107, v107
	v_pk_mul_f32 v[4:5], v[156:157], v[104:105]
	v_pk_mul_f32 v[6:7], v[158:159], v[106:107]
	v_fmac_f32_e32 v235, v100, v100
	v_fmac_f32_e32 v235, v101, v101
	v_fmac_f32_e32 v235, v102, v102
	v_fmac_f32_e32 v235, v103, v103
	v_pk_mul_f32 v[0:1], v[160:161], v[100:101]
	v_pk_mul_f32 v[2:3], v[162:163], v[102:103]
	s_waitcnt lgkmcnt(0)
	ds_read_b128 v[104:107], v237
	ds_read_b128 v[100:103], v237 offset:1024
	v_cvt_pk_bf16_f32 v4, v4, v5
	v_cvt_pk_bf16_f32 v5, v6, v7
	v_cvt_pk_bf16_f32 v6, v0, v1
	v_cvt_pk_bf16_f32 v7, v2, v3
	s_nop 1
	v_permlane16_swap_b32 v4, v6
	v_permlane16_swap_b32 v5, v7
	global_store_dwordx4 v212, v[4:7], s[76:77] offset:256
	s_waitcnt lgkmcnt(0)
	global_store_dwordx4 v214, v[104:107], s[74:75] offset:512
	global_store_dwordx4 v215, v[100:103], s[74:75] offset:512
	v_lshlrev_b32_e32 v214, 2, v231
	v_lshlrev_b32_e32 v215, 2, v232
	ds_bpermute_b32 v164, v214, v216
	ds_bpermute_b32 v165, v214, v217
	ds_bpermute_b32 v166, v214, v218
	ds_bpermute_b32 v167, v214, v219
	ds_bpermute_b32 v168, v214, v228
	ds_bpermute_b32 v169, v214, v229
	ds_bpermute_b32 v170, v214, v234
	ds_bpermute_b32 v171, v214, v235
	s_waitcnt lgkmcnt(0)
	v_add_f32_e32 v216, v216, v164
	v_add_f32_e32 v217, v217, v165
	v_add_f32_e32 v218, v218, v166
	v_add_f32_e32 v219, v219, v167
	v_add_f32_e32 v228, v228, v168
	v_add_f32_e32 v229, v229, v169
	v_add_f32_e32 v234, v234, v170
	v_add_f32_e32 v235, v235, v171
	ds_bpermute_b32 v164, v215, v216
	ds_bpermute_b32 v165, v215, v217
	ds_bpermute_b32 v166, v215, v218
	ds_bpermute_b32 v167, v215, v219
	ds_bpermute_b32 v168, v215, v228
	ds_bpermute_b32 v169, v215, v229
	ds_bpermute_b32 v170, v215, v234
	ds_bpermute_b32 v171, v215, v235
	s_waitcnt lgkmcnt(0)
	v_add_f32_e32 v216, v216, v164
	v_add_f32_e32 v217, v217, v165
	v_add_f32_e32 v218, v218, v166
	v_add_f32_e32 v219, v219, v167
	v_add_f32_e32 v228, v228, v168
	v_add_f32_e32 v229, v229, v169
	v_add_f32_e32 v234, v234, v170
	v_add_f32_e32 v235, v235, v171
	s_and_saveexec_b64 s[44:45], s[40:41]
	s_cbranch_execz .Lresid_noatom
	global_atomic_add_f32 v213, v216, s[6:7] offset:0
	global_atomic_add_f32 v213, v217, s[6:7] offset:64
	global_atomic_add_f32 v213, v218, s[6:7] offset:128
	global_atomic_add_f32 v213, v219, s[6:7] offset:192
	global_atomic_add_f32 v213, v228, s[6:7] offset:512
	global_atomic_add_f32 v213, v229, s[6:7] offset:576
	global_atomic_add_f32 v213, v234, s[6:7] offset:640
	global_atomic_add_f32 v213, v235, s[6:7] offset:704

.Lresid_nonorm:
	v_readlane_b32 s62, v252, 7
	v_readlane_b32 s63, v252, 8
	s_lshr_b32 s20, s56, 4
	s_mul_i32 s20, s20, 0x6000
	s_add_u32 s44, s66, s20
	s_addc_u32 s45, s12, 0
	s_add_u32 s46, s13, s20
	s_addc_u32 s47, s26, 0
	s_mov_b32 s60, s38
	s_mov_b32 s61, s95
	v_lshl_or_b32 v236, s57, 8, v246
	v_lshl_add_u32 v237, s56, 8, v244
	v_lshlrev_b32_e32 v210, 2, v236
	v_lshl_add_u32 v211, v237, 12, v210
	v_and_b32_e32 v212, 4, v246
	v_mul_u32_u24_e32 v212, 6, v212
	v_lshl_add_u32 v212, v236, 1, v212
	v_lshl_add_u32 v212, v237, 11, v212
	v_lshlrev_b32_e32 v213, 2, v237
	v_lshlrev_b32_e32 v214, 2, v231
	v_lshlrev_b32_e32 v215, 2, v232
	v_and_b32_e32 v228, 63, v186
	v_lshrrev_b32_e32 v229, 6, v186
	v_lshlrev_b32_e32 v229, 11, v229
	v_add_u32_e32 v229, 0x20100, v229
	v_lshl_add_u32 v237, v228, 4, v229
	v_and_b32_e32 v236, 15, v244
	v_lshl_add_u32 v236, v236, 7, v229
	v_and_b32_e32 v229, 12, v246
	v_lshl_add_u32 v236, v229, 2, v236
	v_lshrrev_b32_e32 v214, 3, v228
	v_and_b32_e32 v229, 64, v244
	v_add_u32_e32 v214, v214, v229
	v_lshl_add_u32 v214, s56, 8, v214
	v_and_b32_e32 v228, 7, v228
	v_lshlrev_b32_e32 v228, 2, v228
	v_and_b32_e32 v229, 0x60, v246
	v_add_u32_e32 v228, v228, v229
	v_lshl_add_u32 v228, s57, 8, v228
	v_lshlrev_b32_e32 v228, 2, v228
	v_lshl_add_u32 v214, v214, 12, v228
	v_add_u32_e32 v215, 0x8000, v214
	global_load_dwordx4 v[60:63], v210, s[44:45] offset:0
	global_load_dwordx4 v[64:67], v210, s[44:45] offset:64
	global_load_dwordx4 v[68:71], v210, s[44:45] offset:512
	global_load_dwordx4 v[72:75], v210, s[44:45] offset:576
	s_mov_b32 s72, s60
	s_mov_b32 s73, s61
	global_load_dwordx4 v[164:167], v211, s[72:73] offset:0
	global_load_dwordx4 v[168:171], v211, s[72:73] offset:64
	global_load_dwordx4 v[172:175], v211, s[72:73] offset:512
	global_load_dwordx4 v[176:179], v211, s[72:73] offset:576
	s_add_u32 s72, s60, 0x10000
	s_addc_u32 s73, s61, 0
	global_load_dwordx4 v[194:197], v211, s[72:73] offset:0
	global_load_dwordx4 v[198:201], v211, s[72:73] offset:64
	global_load_dwordx4 v[202:205], v211, s[72:73] offset:512
	global_load_dwordx4 v[206:209], v211, s[72:73] offset:576
	s_waitcnt vmcnt(4)
	s_mov_b32 s74, s62
	s_mov_b32 s75, s63
	v_pk_fma_f32 v[164:165], v[144:145], v[60:61], v[164:165]
	v_pk_fma_f32 v[166:167], v[146:147], v[62:63], v[166:167]
	v_pk_fma_f32 v[168:169], v[140:141], v[64:65], v[168:169]
	v_pk_fma_f32 v[170:171], v[142:143], v[66:67], v[170:171]
	ds_write_b128 v236, v[164:167]
	ds_write_b128 v236, v[168:171] offset:64
	s_waitcnt lgkmcnt(0)
	ds_read_b128 v[164:167], v237
	ds_read_b128 v[168:171], v237 offset:1024
	s_waitcnt lgkmcnt(0)
	global_store_dwordx4 v214, v[164:167], s[74:75] offset:0
	global_store_dwordx4 v215, v[168:171], s[74:75] offset:0
	v_pk_fma_f32 v[172:173], v[136:137], v[68:69], v[172:173]
	v_pk_fma_f32 v[174:175], v[138:139], v[70:71], v[174:175]
	v_pk_fma_f32 v[176:177], v[132:133], v[72:73], v[176:177]
	v_pk_fma_f32 v[178:179], v[134:135], v[74:75], v[178:179]
	ds_write_b128 v236, v[172:175]
	ds_write_b128 v236, v[176:179] offset:64
	s_waitcnt lgkmcnt(0)
	ds_read_b128 v[172:175], v237
	ds_read_b128 v[176:179], v237 offset:1024
	s_waitcnt lgkmcnt(0)
	global_store_dwordx4 v214, v[172:175], s[74:75] offset:512
	global_store_dwordx4 v215, v[176:179], s[74:75] offset:512
	s_add_u32 s72, s60, 0x20000
	s_addc_u32 s73, s61, 0
	global_load_dwordx4 v[164:167], v211, s[72:73] offset:0
	global_load_dwordx4 v[168:171], v211, s[72:73] offset:64
	global_load_dwordx4 v[172:175], v211, s[72:73] offset:512
	global_load_dwordx4 v[176:179], v211, s[72:73] offset:576
	s_add_u32 s72, s60, 0x30000
	s_addc_u32 s73, s61, 0
	global_load_dwordx4 v[144:147], v211, s[72:73] offset:0
	global_load_dwordx4 v[140:143], v211, s[72:73] offset:64
	global_load_dwordx4 v[136:139], v211, s[72:73] offset:512
	global_load_dwordx4 v[132:135], v211, s[72:73] offset:576
	s_waitcnt vmcnt(12)
	s_add_u32 s74, s62, 0x10000
	s_addc_u32 s75, s63, 0
	v_pk_fma_f32 v[194:195], v[128:129], v[60:61], v[194:195]
	v_pk_fma_f32 v[196:197], v[130:131], v[62:63], v[196:197]
	v_pk_fma_f32 v[198:199], v[124:125], v[64:65], v[198:199]
	v_pk_fma_f32 v[200:201], v[126:127], v[66:67], v[200:201]
	ds_write_b128 v236, v[194:197]
	ds_write_b128 v236, v[198:201] offset:64
	s_waitcnt lgkmcnt(0)
	ds_read_b128 v[194:197], v237
	ds_read_b128 v[198:201], v237 offset:1024
	s_waitcnt lgkmcnt(0)
	global_store_dwordx4 v214, v[194:197], s[74:75] offset:0
	global_store_dwordx4 v215, v[198:201], s[74:75] offset:0
	v_pk_fma_f32 v[202:203], v[120:121], v[68:69], v[202:203]
	v_pk_fma_f32 v[204:205], v[122:123], v[70:71], v[204:205]
	v_pk_fma_f32 v[206:207], v[116:117], v[72:73], v[206:207]
	v_pk_fma_f32 v[208:209], v[118:119], v[74:75], v[208:209]
	ds_write_b128 v236, v[202:205]
	ds_write_b128 v236, v[206:209] offset:64
	s_waitcnt lgkmcnt(0)
	ds_read_b128 v[202:205], v237
	ds_read_b128 v[206:209], v237 offset:1024
	s_waitcnt lgkmcnt(0)
	global_store_dwordx4 v214, v[202:205], s[74:75] offset:512
	global_store_dwordx4 v215, v[206:209], s[74:75] offset:512
	s_add_u32 s72, s60, 0x80000
	s_addc_u32 s73, s61, 0
	global_load_dwordx4 v[194:197], v211, s[72:73] offset:0
	global_load_dwordx4 v[198:201], v211, s[72:73] offset:64
	global_load_dwordx4 v[202:205], v211, s[72:73] offset:512
	global_load_dwordx4 v[206:209], v211, s[72:73] offset:576
	s_add_u32 s72, s60, 0x90000
	s_addc_u32 s73, s61, 0
	global_load_dwordx4 v[128:131], v211, s[72:73] offset:0
	global_load_dwordx4 v[124:127], v211, s[72:73] offset:64
	global_load_dwordx4 v[120:123], v211, s[72:73] offset:512
	global_load_dwordx4 v[116:119], v211, s[72:73] offset:576
	s_waitcnt vmcnt(16)
	s_add_u32 s74, s62, 0x20000
	s_addc_u32 s75, s63, 0
	v_pk_fma_f32 v[164:165], v[112:113], v[60:61], v[164:165]
	v_pk_fma_f32 v[166:167], v[114:115], v[62:63], v[166:167]
	v_pk_fma_f32 v[168:169], v[108:109], v[64:65], v[168:169]
	v_pk_fma_f32 v[170:171], v[110:111], v[66:67], v[170:171]
	ds_write_b128 v236, v[164:167]
	ds_write_b128 v236, v[168:171] offset:64
	s_waitcnt lgkmcnt(0)
	ds_read_b128 v[164:167], v237
	ds_read_b128 v[168:171], v237 offset:1024
	s_waitcnt lgkmcnt(0)
	global_store_dwordx4 v214, v[164:167], s[74:75] offset:0
	global_store_dwordx4 v215, v[168:171], s[74:75] offset:0
	v_pk_fma_f32 v[172:173], v[104:105], v[68:69], v[172:173]
	v_pk_fma_f32 v[174:175], v[106:107], v[70:71], v[174:175]
	v_pk_fma_f32 v[176:177], v[100:101], v[72:73], v[176:177]
	v_pk_fma_f32 v[178:179], v[102:103], v[74:75], v[178:179]
	ds_write_b128 v236, v[172:175]
	ds_write_b128 v236, v[176:179] offset:64
	s_waitcnt lgkmcnt(0)
	ds_read_b128 v[172:175], v237
	ds_read_b128 v[176:179], v237 offset:1024
	s_waitcnt lgkmcnt(0)
	global_store_dwordx4 v214, v[172:175], s[74:75] offset:512
	global_store_dwordx4 v215, v[176:179], s[74:75] offset:512
	s_add_u32 s72, s60, 0xa0000
	s_addc_u32 s73, s61, 0
	global_load_dwordx4 v[164:167], v211, s[72:73] offset:0
	global_load_dwordx4 v[168:171], v211, s[72:73] offset:64
	global_load_dwordx4 v[172:175], v211, s[72:73] offset:512
	global_load_dwordx4 v[176:179], v211, s[72:73] offset:576
	s_add_u32 s72, s60, 0xb0000
	s_addc_u32 s73, s61, 0
	global_load_dwordx4 v[112:115], v211, s[72:73] offset:0
	global_load_dwordx4 v[108:111], v211, s[72:73] offset:64
	global_load_dwordx4 v[104:107], v211, s[72:73] offset:512
	global_load_dwordx4 v[100:103], v211, s[72:73] offset:576
	s_waitcnt vmcnt(24)
	s_add_u32 s74, s62, 0x30000
	s_addc_u32 s75, s63, 0
	v_pk_fma_f32 v[144:145], v[92:93], v[60:61], v[144:145]
	v_pk_fma_f32 v[146:147], v[94:95], v[62:63], v[146:147]
	v_pk_fma_f32 v[140:141], v[88:89], v[64:65], v[140:141]
	v_pk_fma_f32 v[142:143], v[90:91], v[66:67], v[142:143]
	ds_write_b128 v236, v[144:147]
	ds_write_b128 v236, v[140:143] offset:64
	s_waitcnt lgkmcnt(0)
	ds_read_b128 v[144:147], v237
	ds_read_b128 v[140:143], v237 offset:1024
	s_waitcnt lgkmcnt(0)
	global_store_dwordx4 v214, v[144:147], s[74:75] offset:0
	global_store_dwordx4 v215, v[140:143], s[74:75] offset:0
	v_pk_fma_f32 v[136:137], v[84:85], v[68:69], v[136:137]
	v_pk_fma_f32 v[138:139], v[86:87], v[70:71], v[138:139]
	v_pk_fma_f32 v[132:133], v[80:81], v[72:73], v[132:133]
	v_pk_fma_f32 v[134:135], v[82:83], v[74:75], v[134:135]
	ds_write_b128 v236, v[136:139]
	ds_write_b128 v236, v[132:135] offset:64
	s_waitcnt lgkmcnt(0)
	ds_read_b128 v[136:139], v237
	ds_read_b128 v[132:135], v237 offset:1024
	s_waitcnt lgkmcnt(0)
	global_store_dwordx4 v214, v[136:139], s[74:75] offset:512
	global_store_dwordx4 v215, v[132:135], s[74:75] offset:512
	s_waitcnt vmcnt(20)
	s_add_u32 s74, s62, 0x80000
	s_addc_u32 s75, s63, 0
	v_pk_fma_f32 v[194:195], v[76:77], v[60:61], v[194:195]
	v_pk_fma_f32 v[196:197], v[78:79], v[62:63], v[196:197]
	v_pk_fma_f32 v[198:199], v[56:57], v[64:65], v[198:199]
	v_pk_fma_f32 v[200:201], v[58:59], v[66:67], v[200:201]
	ds_write_b128 v236, v[194:197]
	ds_write_b128 v236, v[198:201] offset:64
	s_waitcnt lgkmcnt(0)
	ds_read_b128 v[194:197], v237
	ds_read_b128 v[198:201], v237 offset:1024
	s_waitcnt lgkmcnt(0)
	global_store_dwordx4 v214, v[194:197], s[74:75] offset:0
	global_store_dwordx4 v215, v[198:201], s[74:75] offset:0
	v_pk_fma_f32 v[202:203], v[52:53], v[68:69], v[202:203]
	v_pk_fma_f32 v[204:205], v[54:55], v[70:71], v[204:205]
	v_pk_fma_f32 v[206:207], v[48:49], v[72:73], v[206:207]
	v_pk_fma_f32 v[208:209], v[50:51], v[74:75], v[208:209]
	ds_write_b128 v236, v[202:205]
	ds_write_b128 v236, v[206:209] offset:64
	s_waitcnt lgkmcnt(0)
	ds_read_b128 v[202:205], v237
	ds_read_b128 v[206:209], v237 offset:1024
	s_waitcnt lgkmcnt(0)
	global_store_dwordx4 v214, v[202:205], s[74:75] offset:512
	global_store_dwordx4 v215, v[206:209], s[74:75] offset:512
	s_waitcnt vmcnt(20)
	s_add_u32 s74, s62, 0x90000
	s_addc_u32 s75, s63, 0
	v_pk_fma_f32 v[128:129], v[44:45], v[60:61], v[128:129]
	v_pk_fma_f32 v[130:131], v[46:47], v[62:63], v[130:131]
	v_pk_fma_f32 v[124:125], v[40:41], v[64:65], v[124:125]
	v_pk_fma_f32 v[126:127], v[42:43], v[66:67], v[126:127]
	ds_write_b128 v236, v[128:131]
	ds_write_b128 v236, v[124:127] offset:64
	s_waitcnt lgkmcnt(0)
	ds_read_b128 v[128:131], v237
	ds_read_b128 v[124:127], v237 offset:1024
	s_waitcnt lgkmcnt(0)
	global_store_dwordx4 v214, v[128:131], s[74:75] offset:0
	global_store_dwordx4 v215, v[124:127], s[74:75] offset:0
	v_pk_fma_f32 v[120:121], v[36:37], v[68:69], v[120:121]
	v_pk_fma_f32 v[122:123], v[38:39], v[70:71], v[122:123]
	v_pk_fma_f32 v[116:117], v[32:33], v[72:73], v[116:117]
	v_pk_fma_f32 v[118:119], v[34:35], v[74:75], v[118:119]
	ds_write_b128 v236, v[120:123]
	ds_write_b128 v236, v[116:119] offset:64
	s_waitcnt lgkmcnt(0)
	ds_read_b128 v[120:123], v237
	ds_read_b128 v[116:119], v237 offset:1024
	s_waitcnt lgkmcnt(0)
	global_store_dwordx4 v214, v[120:123], s[74:75] offset:512
	global_store_dwordx4 v215, v[116:119], s[74:75] offset:512
	s_waitcnt vmcnt(16)
	s_add_u32 s74, s62, 0xa0000
	s_addc_u32 s75, s63, 0
	v_pk_fma_f32 v[164:165], v[28:29], v[60:61], v[164:165]
	v_pk_fma_f32 v[166:167], v[30:31], v[62:63], v[166:167]
	v_pk_fma_f32 v[168:169], v[24:25], v[64:65], v[168:169]
	v_pk_fma_f32 v[170:171], v[26:27], v[66:67], v[170:171]
	ds_write_b128 v236, v[164:167]
	ds_write_b128 v236, v[168:171] offset:64
	s_waitcnt lgkmcnt(0)
	ds_read_b128 v[164:167], v237
	ds_read_b128 v[168:171], v237 offset:1024
	s_waitcnt lgkmcnt(0)
	global_store_dwordx4 v214, v[164:167], s[74:75] offset:0
	global_store_dwordx4 v215, v[168:171], s[74:75] offset:0
	v_pk_fma_f32 v[172:173], v[20:21], v[68:69], v[172:173]
	v_pk_fma_f32 v[174:175], v[22:23], v[70:71], v[174:175]
	v_pk_fma_f32 v[176:177], v[16:17], v[72:73], v[176:177]
	v_pk_fma_f32 v[178:179], v[18:19], v[74:75], v[178:179]
	ds_write_b128 v236, v[172:175]
	ds_write_b128 v236, v[176:179] offset:64
	s_waitcnt lgkmcnt(0)
	ds_read_b128 v[172:175], v237
	ds_read_b128 v[176:179], v237 offset:1024
	s_waitcnt lgkmcnt(0)
	global_store_dwordx4 v214, v[172:175], s[74:75] offset:512
	global_store_dwordx4 v215, v[176:179], s[74:75] offset:512
	s_waitcnt vmcnt(16)
	s_add_u32 s74, s62, 0xb0000
	s_addc_u32 s75, s63, 0
	v_pk_fma_f32 v[112:113], v[12:13], v[60:61], v[112:113]
	v_pk_fma_f32 v[114:115], v[14:15], v[62:63], v[114:115]
	v_pk_fma_f32 v[108:109], v[8:9], v[64:65], v[108:109]
	v_pk_fma_f32 v[110:111], v[10:11], v[66:67], v[110:111]
	ds_write_b128 v236, v[112:115]
	ds_write_b128 v236, v[108:111] offset:64
	s_waitcnt lgkmcnt(0)
	ds_read_b128 v[112:115], v237
	ds_read_b128 v[108:111], v237 offset:1024
	s_waitcnt lgkmcnt(0)
	global_store_dwordx4 v214, v[112:115], s[74:75] offset:0
	global_store_dwordx4 v215, v[108:111], s[74:75] offset:0
	v_pk_fma_f32 v[104:105], v[4:5], v[68:69], v[104:105]
	v_pk_fma_f32 v[106:107], v[6:7], v[70:71], v[106:107]
	v_pk_fma_f32 v[100:101], v[0:1], v[72:73], v[100:101]
	v_pk_fma_f32 v[102:103], v[2:3], v[74:75], v[102:103]
	ds_write_b128 v236, v[104:107]
	ds_write_b128 v236, v[100:103] offset:64
	s_waitcnt lgkmcnt(0)
	ds_read_b128 v[104:107], v237
	ds_read_b128 v[100:103], v237 offset:1024
	s_waitcnt lgkmcnt(0)
	global_store_dwordx4 v214, v[104:107], s[74:75] offset:512
	global_store_dwordx4 v215, v[100:103], s[74:75] offset:512
	s_branch .Lresid_done

	.amdhsa_kernel _Z6mk_fwd4Args
		.amdhsa_group_segment_fixed_size 16384
		.amdhsa_private_segment_fixed_size 0
		.amdhsa_kernarg_size 432
		.amdhsa_user_sgpr_count 2
		.amdhsa_user_sgpr_dispatch_ptr 0
		.amdhsa_user_sgpr_queue_ptr 0
		.amdhsa_user_sgpr_kernarg_segment_ptr 1
		.amdhsa_user_sgpr_dispatch_id 0
		.amdhsa_user_sgpr_kernarg_preload_length 0
		.amdhsa_user_sgpr_kernarg_preload_offset 0
		.amdhsa_user_sgpr_private_segment_size 0
		.amdhsa_uses_dynamic_stack 0
		.amdhsa_enable_private_segment 0
		.amdhsa_system_sgpr_workgroup_id_x 1
		.amdhsa_system_sgpr_workgroup_id_y 0
		.amdhsa_system_sgpr_workgroup_id_z 0
		.amdhsa_system_sgpr_workgroup_info 0
		.amdhsa_system_vgpr_workitem_id 2
		.amdhsa_next_free_vgpr 256
		.amdhsa_next_free_sgpr 100
		.amdhsa_accum_offset 256
		.amdhsa_reserve_vcc 1
		.amdhsa_float_round_mode_32 0
		.amdhsa_float_round_mode_16_64 0
		.amdhsa_float_denorm_mode_32 3
		.amdhsa_float_denorm_mode_16_64 3
		.amdhsa_dx10_clamp 1
		.amdhsa_ieee_mode 1
		.amdhsa_fp16_overflow 0
		.amdhsa_tg_split 0
		.amdhsa_exception_fp_ieee_invalid_op 0
		.amdhsa_exception_fp_denorm_src 0
		.amdhsa_exception_fp_ieee_div_zero 0
		.amdhsa_exception_fp_ieee_overflow 0
		.amdhsa_exception_fp_ieee_underflow 0
		.amdhsa_exception_fp_ieee_inexact 0
		.amdhsa_exception_int_div_zero 0
	.end_amdhsa_kernel

amdhsa.kernels:
  - .agpr_count:     0
    .args:
      - .offset:         0
        .size:           176
        .value_kind:     by_value
      - .offset:         176
        .size:           4
        .value_kind:     hidden_block_count_x
      - .offset:         180
        .size:           4
        .value_kind:     hidden_block_count_y
      - .offset:         184
        .size:           4
        .value_kind:     hidden_block_count_z
      - .offset:         188
        .size:           2
        .value_kind:     hidden_group_size_x
      - .offset:         190
        .size:           2
        .value_kind:     hidden_group_size_y
      - .offset:         192
        .size:           2
        .value_kind:     hidden_group_size_z
      - .offset:         194
        .size:           2
        .value_kind:     hidden_remainder_x
      - .offset:         196
        .size:           2
        .value_kind:     hidden_remainder_y
      - .offset:         198
        .size:           2
        .value_kind:     hidden_remainder_z
      - .offset:         216
        .size:           8
        .value_kind:     hidden_global_offset_x
      - .offset:         224
        .size:           8
        .value_kind:     hidden_global_offset_y
      - .offset:         232
        .size:           8
        .value_kind:     hidden_global_offset_z
      - .offset:         240
        .size:           2
        .value_kind:     hidden_grid_dims
      - .offset:         264
        .size:           8
        .value_kind:     hidden_multigrid_sync_arg
      - .offset:         296
        .size:           4
        .value_kind:     hidden_dynamic_lds_size
    .group_segment_fixed_size: 16384
    .kernarg_segment_align: 8
    .kernarg_segment_size: 432
    .language:       OpenCL C
    .language_version:
      - 2
      - 0
    .max_flat_workgroup_size: 512
    .name:           _Z6mk_fwd4Args
    .private_segment_fixed_size: 0
    .sgpr_count:     106
    .sgpr_spill_count: 387
    .symbol:         _Z6mk_fwd4Args.kd
    .uniform_work_group_size: 1
    .uses_dynamic_stack: false
    .vgpr_count:     256
    .vgpr_spill_count: 0
    .wavefront_size: 64
